# P1: workgroups with 3 tiles run the leftover weight conversions before their tiles (their store bursts interleave with the 4-tile half); on top of fused combine pass
# speedup vs baseline: 1.0339x; 1.0113x over previous
.LBB0_152:
	s_mov_b32 s101, 0
	s_cmp_lt_i32 s30, 2
	s_cselect_b64 s[2:3], -1, 0
	s_waitcnt lgkmcnt(0)
	s_add_u32 s38, s28, 0x6000000
	s_addc_u32 s39, s29, 0
	s_and_b64 s[18:19], s[2:3], s[0:1]
	s_andn2_b64 vcc, exec, s[18:19]
	s_cbranch_vccnz .LBB0_237
	s_cmpk_lt_i32 s70, 0x80
	s_cbranch_scc1 .Lp1_gemm_entry
	s_cmpk_lg_i32 s17, 0x100
	s_cbranch_scc1 .Lp1_gemm_entry
	s_cmp_lg_u32 s30, 0
	s_cbranch_scc1 .Lp1_gemm_entry
	s_mov_b32 s101, 1
	s_branch .Lp1_tr_entry
.Lp1_after_tr:
	s_mov_b32 s101, 2
	s_add_u32 s4, s28, 0x100000
	s_addc_u32 s5, s29, 0
	s_waitcnt lgkmcnt(0)
	s_barrier
.Lp1_gemm_entry:
	s_cmpk_gt_i32 s70, 0x37f
	v_readfirstlane_b32 s3, v189
	s_cbranch_scc1 .LBB0_169
	v_lshrrev_b32_e32 v2, 1, v189
	s_waitcnt vmcnt(1)
	v_and_b32_e32 v11, 24, v2
	v_lshrrev_b32_e32 v2, 5, v189
	v_and_b32_e32 v2, 4, v2
	v_bfe_u32 v3, v189, 2, 2
	v_lshlrev_b32_e32 v0, 4, v189
	v_and_b32_e32 v1, 32, v189
	v_bfe_u32 v10, v189, 2, 4
	v_or3_b32 v2, v2, v3, v11
	v_lshrrev_b32_e32 v3, 3, v189
	s_movk_i32 s0, 0x70
	v_bitop3_b32 v8, v0, v1, 48 bitop3:0x6c
	v_and_b32_e32 v9, 64, v189
	v_and_or_b32 v4, v3, s0, v10
	s_movk_i32 s0, 0x60
	s_waitcnt vmcnt(0)
	v_add_u32_e32 v12, 0x2000, v0
	v_or_b32_e32 v1, v8, v9
	v_and_or_b32 v3, v3, s0, v2
	v_lshrrev_b32_e32 v0, 7, v12
	s_movk_i32 s0, 0xf0
	v_lshl_or_b32 v130, v3, 11, v1
	v_and_or_b32 v3, v0, s0, v10
	s_movk_i32 s0, 0xe0
	s_ashr_i32 s96, s70, 31
	v_and_or_b32 v0, v0, s0, v2
	s_lshr_b32 s0, s96, 29
	s_add_i32 s0, s70, s0
	s_lshr_b32 s8, s3, 6
	s_ashr_i32 s1, s0, 3
	s_and_b32 s0, s0, -8
	s_lshr_b32 s10, s3, 8
	s_lshl_b32 s75, s8, 10
	s_sub_i32 s0, s70, s0
	s_cmp_lt_i32 s0, 0
	s_movk_i32 s2, 0x71
	s_cselect_b32 s2, s2, 0x70
	s_mul_i32 s0, s0, s2
	s_add_i32 s0, s0, s1
	s_mul_hi_i32 s1, s0, 0x92492493
	s_add_i32 s1, s1, s0
	s_lshr_b32 s2, s1, 31
	s_ashr_i32 s1, s1, 5
	s_add_i32 s1, s1, s2
	s_lshl_b32 s6, s1, 3
	s_mul_i32 s1, s1, 56
	s_sub_i32 s0, s0, s1
	s_bfe_i32 s1, s0, 0x80000
	s_bfe_u32 s1, s1, 0x3000c
	s_add_i32 s1, s0, s1
	s_bfe_i32 s2, s1, 0x80000
	s_and_b32 s1, s1, 0xf8
	s_sub_i32 s0, s0, s1
	s_sext_i32_i16 s2, s2
	s_sext_i32_i8 s0, s0
	s_lshr_b32 s2, s2, 3
	s_add_i32 s84, s6, s0
	s_ashr_i32 s85, s84, 31
	s_bfe_i64 s[12:13], s[2:3], 0x100000
	s_lshl_b64 s[6:7], s[84:85], 19
	s_lshl_b64 s[12:13], s[12:13], 19
	s_add_u32 s88, s4, s12
	s_addc_u32 s89, s5, s13
	s_add_i32 s85, s75, 0
	s_add_i32 m0, s85, 0x10000
	v_writelane_b32 v255, s18, 9
	global_load_lds_dwordx4 v130, s[88:89]
	s_add_i32 m0, s85, 0x12000
	v_writelane_b32 v255, s19, 10
	v_lshl_or_b32 v134, v0, 11, v1
	s_add_u32 s12, s88, 0x40000
	v_writelane_b32 v255, s33, 11
	global_load_lds_dwordx4 v134, s[88:89]
	s_addc_u32 s13, s89, 0
	s_add_i32 m0, s85, 0x14000
	v_writelane_b32 v255, s16, 12
	global_load_lds_dwordx4 v130, s[12:13]
	s_add_i32 m0, s85, 0x16000
	v_writelane_b32 v255, s76, 13
	s_add_u32 s86, s34, s6
	s_addc_u32 s87, s35, s7
	v_writelane_b32 v255, s77, 14
	s_add_i32 s76, s85, 0x2000
	v_lshl_or_b32 v128, v4, 11, v1
	global_load_lds_dwordx4 v134, s[12:13]
	s_mov_b32 m0, s85
	s_add_u32 s6, s86, 0x40000
	v_lshl_or_b32 v132, v3, 11, v1
	global_load_lds_dwordx4 v128, s[86:87]
	s_mov_b32 m0, s76
	s_addc_u32 s7, s87, 0
	s_add_i32 s77, s85, 0x4000
	global_load_lds_dwordx4 v132, s[86:87]
	s_mov_b32 m0, s77
	s_add_i32 s68, s85, 0x6000
	global_load_lds_dwordx4 v128, s[6:7]
	s_mov_b32 m0, s68
	v_mov_b32_e32 v131, 0
	global_load_lds_dwordx4 v132, s[6:7]
	v_writelane_b32 v255, s72, 15
	v_mov_b32_e32 v135, v131
	v_mov_b32_e32 v129, v131
	v_mov_b32_e32 v133, v131
	s_cmp_eq_u32 s10, 1
	v_writelane_b32 v255, s73, 16
	s_mov_b32 s69, 0
	v_lshl_add_u64 v[6:7], s[88:89], 0, v[130:131]
	v_lshl_add_u64 v[4:5], s[88:89], 0, v[134:135]
	v_lshl_add_u64 v[0:1], s[86:87], 0, v[128:129]
	s_cselect_b64 s[6:7], -1, 0
	s_cmp_lg_u32 s10, 1
	v_lshl_add_u64 v[2:3], s[86:87], 0, v[132:133]
	s_cbranch_scc1 .LBB0_156
	s_barrier

.LBB0_169:
	s_cmp_eq_u32 s101, 2
	s_cbranch_scc1 .LBB0_237
	s_cmpk_lg_i32 s17, 0x100
	s_cselect_b64 s[0:1], -1, 0
	s_cmp_lg_u32 s30, 0
	s_cselect_b64 s[2:3], -1, 0
	s_or_b64 s[0:1], s[0:1], s[2:3]
	s_cmpk_lt_i32 s70, 0x80
	s_cselect_b64 s[2:3], -1, 0
	s_or_b64 s[0:1], s[2:3], s[0:1]
	s_and_b64 vcc, exec, s[0:1]
	s_cbranch_vccnz .LBB0_237
.Lp1_tr_entry:
	s_lshl_b32 s0, s70, 3
	s_add_i32 s2, s33, s0
	s_addk_i32 s2, 0xfc00
	s_cmpk_gt_i32 s2, 0x127f
	s_waitcnt vmcnt(0)
	s_barrier
	s_cbranch_scc1 .LBB0_237
	s_lshl_b32 s0, s33, 14
	v_lshrrev_b32_e32 v62, 3, v240
	v_and_b32_e32 v0, 7, v189
	s_add_i32 s0, s0, 0
	v_lshlrev_b32_e32 v36, 4, v0
	v_mul_u32_u24_e32 v0, 0x420, v0
	v_lshlrev_b32_e32 v2, 2, v62
	v_add_u32_e32 v63, s0, v36
	v_add3_u32 v67, s0, v0, v2
	v_readlane_b32 s0, v255, 6
	v_mov_b32_e32 v37, 0
	v_readlane_b32 s1, v255, 7
	s_add_i32 s12, s2, 0x380
	v_mul_u32_u24_e32 v1, 0x84, v62
	v_lshl_add_u64 v[40:41], s[0:1], 0, v[36:37]
	v_readlane_b32 s0, v255, 4
	v_readlane_b32 s1, v255, 5
	s_cmp_lg_u64 s[66:67], 0
	v_or_b32_e32 v0, 32, v62
	v_lshl_add_u64 v[44:45], s[0:1], 0, v[36:37]
	v_readlane_b32 s0, v255, 2
	v_readlane_b32 s1, v255, 3
	v_lshl_add_u64 v[54:55], s[4:5], 0, v[36:37]
	s_cselect_b64 s[4:5], -1, 0
	s_cmp_eq_u64 s[60:61], 0
	v_add_u32_e32 v69, v63, v1
	s_mov_b32 s7, 0
	v_or_b32_e32 v64, 8, v62
	v_or_b32_e32 v65, 16, v62
	v_or_b32_e32 v66, 24, v62
	v_mul_u32_u24_e32 v68, 0x84, v0
	v_lshl_add_u64 v[38:39], s[24:25], 0, v[36:37]
	v_lshl_add_u64 v[42:43], s[22:23], 0, v[36:37]
	v_lshl_add_u64 v[46:47], s[20:21], 0, v[36:37]
	v_lshl_add_u64 v[48:49], s[64:65], 0, v[36:37]
	v_lshl_add_u64 v[50:51], s[0:1], 0, v[36:37]
	v_lshl_add_u64 v[52:53], s[40:41], 0, v[36:37]
	s_cselect_b64 s[8:9], -1, 0
	s_lshl_b32 s13, s12, 5
	s_lshl_b32 s20, s12, 1
	v_add_u32_e32 v70, 0x420, v69
	v_add_u32_e32 v71, 0x428, v69
	v_add_u32_e32 v72, 0x840, v69
	v_add_u32_e32 v73, 0x848, v69
	v_add_u32_e32 v74, 0xc60, v69
	v_add_u32_e32 v75, 0xc68, v69
	v_add_u32_e32 v76, 0x1080, v69
	v_add_u32_e32 v77, 0x1088, v69
	v_add_u32_e32 v78, 0x14a0, v69
	v_add_u32_e32 v79, 0x14a8, v69
	v_add_u32_e32 v80, 0x18c0, v69
	v_add_u32_e32 v81, 0x18c8, v69
	v_add_u32_e32 v82, 0x1ce0, v69
	v_add_u32_e32 v83, 0x1ce8, v69
	s_movk_i32 s21, 0x2c00
	s_mov_b32 s22, 0x16000
	s_mov_b32 s23, 0x2c000
	s_mov_b32 s24, 0x42000
	s_mov_b32 s25, 0x58000
	s_movk_i32 s40, 0x1c00
	s_branch .LBB0_173

.LBB0_237:
	s_cmp_eq_u32 s101, 1
	s_cbranch_scc1 .Lp1_after_tr
	s_cmp_gt_i32 s31, 2
	s_cselect_b64 s[2:3], -1, 0
	s_and_b64 s[0:1], s[18:19], s[2:3]
	s_andn2_b64 vcc, exec, s[0:1]
	s_cbranch_vccnz .LBB0_287
	s_waitcnt vmcnt(0)
	v_cmp_eq_u32_e32 vcc, 0, v189
	s_waitcnt vmcnt(0)
	s_barrier
	s_and_saveexec_b64 s[0:1], vcc
	s_cbranch_execz .LBB0_286
	s_add_i32 s4, 0, 0x20020
	v_mov_b32_e32 v0, s4
	s_waitcnt vmcnt(0) expcnt(0) lgkmcnt(0)
	ds_read_b32 v2, v0
	s_add_i32 s4, 0, 0x20024
	v_mov_b32_e32 v0, s4
	ds_read_b32 v0, v0
	s_waitcnt lgkmcnt(1)
	v_cmp_ne_u32_e32 vcc, 0, v2
	s_cbranch_vccnz .LBB0_254
	v_readlane_b32 s4, v255, 0
	v_readlane_b32 s5, v255, 1
	s_load_dwordx2 s[8:9], s[4:5], 0x4
	s_add_u32 s4, s28, 0x1000
	s_addc_u32 s5, s29, 0
	s_add_u32 s6, s28, 0x1100
	s_addc_u32 s7, s29, 0
	s_waitcnt lgkmcnt(0)
	s_mul_i32 s14, s8, s17
	s_add_u32 s8, s28, 0x1200
	s_mul_i32 s14, s14, s9
	s_addc_u32 s9, s29, 0
	s_add_u32 s10, s28, 0x1300
	s_addc_u32 s11, s29, 0
	s_mov_b32 s15, 1
	v_mov_b32_e32 v16, 0
	s_branch .LBB0_242
